# attention: next tile K fragments read from LDS at the end of the iteration (overlapping the V DMA issue)
# baseline (speedup 1.0000x reference)
.LBB0_1133:
	s_lshl_b32 s0, s2, 3
	v_readlane_b32 s1, v255, 36
	s_or_b32 s3, s0, s1
	v_readlane_b32 s0, v255, 34
	v_readlane_b32 s1, v255, 35
	s_and_b64 s[0:1], s[0:1], exec
	s_cselect_b32 s82, s3, s2
	s_ashr_i32 s83, s82, 31
	s_lshl_b64 s[70:71], s[82:83], 19
	s_lshl_b64 s[78:79], s[82:83], 20
	v_readlane_b32 s0, v255, 37
	s_add_u32 s0, s0, s78
	v_readlane_b32 s1, v255, 38
	s_addc_u32 s1, s1, s79
	v_readlane_b32 s2, v255, 43
	s_add_u32 s2, s2, s78
	v_readlane_b32 s3, v255, 44
	v_add_u32_e32 v2, s73, v157
	s_addc_u32 s3, s3, s79
	v_readlane_b32 s76, v255, 45
	v_ashrrev_i32_e32 v0, 31, v2
	s_add_u32 vcc_lo, s76, s78
	v_readlane_b32 s76, v255, 46
	v_mul_lo_u32 v3, s74, v0
	v_mov_b64_e32 v[0:1], s[84:85]
	s_addc_u32 vcc_hi, s76, s79
	v_mad_u64_u32 v[150:151], s[78:79], s74, v2, v[0:1]
	s_sub_i32 s78, 0x80, s73
	s_lshr_b32 s78, s78, 5
	s_cmpk_lt_i32 s73, 0x80
	s_cselect_b32 s81, s78, 0
	s_lshl_b32 s78, s81, 5
	s_add_i32 s76, s78, s73
	s_add_i32 s94, s76, 0xffffff80
	v_mul_lo_u32 v0, s75, v2
	v_add_u32_e32 v2, s94, v158
	v_add3_u32 v151, v0, v151, v3
	v_ashrrev_i32_e32 v0, 31, v2
	v_mul_lo_u32 v3, s74, v0
	v_mov_b64_e32 v[0:1], s[84:85]
	v_mul_lo_u32 v4, s75, v2
	v_mad_u64_u32 v[0:1], s[78:79], s74, v2, v[0:1]
	v_add3_u32 v1, v4, v1, v3
	v_lshlrev_b64 v[0:1], 8, v[0:1]
	v_lshl_add_u64 v[0:1], vcc, 0, v[0:1]
	s_add_i32 m0, s90, 0x2000
	v_lshl_add_u64 v[0:1], v[0:1], 0, v[188:189]
	s_lshl_b64 s[96:97], s[74:75], 12
	global_load_lds_dwordx4 v[0:1], off
	v_lshl_add_u64 v[2:3], v[0:1], 0, s[96:97]
	s_add_i32 m0, s90, 0x2400
	v_lshl_add_u64 v[4:5], v[0:1], 0, 64
	global_load_lds_dwordx4 v[2:3], off
	s_add_i32 m0, s90, 0x2800
	s_mov_b64 s[78:79], 0xc0
	global_load_lds_dwordx4 v[4:5], off
	v_lshl_add_u64 v[4:5], v[2:3], 0, 64
	s_add_i32 m0, s90, 0x2c00
	v_mov_b32_e32 v145, v189
	global_load_lds_dwordx4 v[4:5], off
	v_lshl_add_u64 v[4:5], v[0:1], 0, s[88:89]
	s_add_i32 m0, s90, 0x3000
	v_lshl_add_u64 v[0:1], v[0:1], 0, s[78:79]
	global_load_lds_dwordx4 v[4:5], off
	v_lshl_add_u64 v[4:5], v[2:3], 0, s[88:89]
	s_add_i32 m0, s90, 0x3400
	v_mov_b32_e32 v147, v189
	global_load_lds_dwordx4 v[4:5], off
	s_add_i32 m0, s90, 0x3800
	v_mov_b32_e32 v14, v189
	global_load_lds_dwordx4 v[0:1], off
	v_lshl_add_u64 v[0:1], v[2:3], 0, s[78:79]
	s_add_i32 m0, s90, 0x3c00
	s_nop 0
	global_load_lds_dwordx4 v[0:1], off
	v_add_u32_e32 v2, s94, v158
	v_ashrrev_i32_e32 v116, 31, v2
	v_mov_b64_e32 v[112:113], s[84:85]
	v_mad_u64_u32 v[114:115], s[78:79], s74, v2, v[112:113]
	v_mul_lo_u32 v117, s75, v2
	v_mul_lo_u32 v116, s74, v116
	v_add3_u32 v115, v117, v115, v116
	v_lshlrev_b64 v[114:115], 8, v[114:115]
	v_lshl_add_u64 v[114:115], s[2:3], 0, v[114:115]
	v_lshl_add_u64 v[114:115], v[114:115], 0, v[198:199]
	s_mov_b32 m0, s90
	v_lshl_add_u64 v[116:117], v[114:115], 0, s[96:97]
	global_load_lds_dwordx4 v[114:115], off
	s_add_i32 m0, s90, 0x400
	v_lshl_add_u64 v[118:119], v[114:115], 0, 64
	global_load_lds_dwordx4 v[116:117], off
	s_add_i32 m0, s90, 0x800
	s_nop 0
	global_load_lds_dwordx4 v[118:119], off
	v_lshl_add_u64 v[118:119], v[116:117], 0, 64
	s_add_i32 m0, s90, 0xc00
	s_nop 0
	global_load_lds_dwordx4 v[118:119], off
	v_lshl_add_u64 v[118:119], v[114:115], 0, s[88:89]
	s_add_i32 m0, s90, 0x1000
	v_lshl_add_u64 v[114:115], v[114:115], 0, s[100:101]
	global_load_lds_dwordx4 v[118:119], off
	v_lshl_add_u64 v[118:119], v[116:117], 0, s[88:89]
	s_add_i32 m0, s90, 0x1400
	s_nop 0
	global_load_lds_dwordx4 v[118:119], off
	s_add_i32 m0, s90, 0x1800
	s_nop 0
	global_load_lds_dwordx4 v[114:115], off
	v_lshl_add_u64 v[114:115], v[116:117], 0, s[100:101]
	s_add_i32 m0, s90, 0x1c00
	s_nop 0
	global_load_lds_dwordx4 v[114:115], off
	v_lshlrev_b64 v[0:1], 8, v[150:151]
	v_lshl_add_u64 v[0:1], s[0:1], 0, v[0:1]
	v_lshl_add_u64 v[0:1], v[0:1], 0, v[146:147]
	global_load_dwordx4 v[80:83], v[0:1], off
	global_load_dwordx4 v[84:87], v[0:1], off offset:32
	global_load_dwordx4 v[88:91], v[0:1], off offset:64
	global_load_dwordx4 v[92:95], v[0:1], off offset:96
	global_load_dwordx4 v[96:99], v[0:1], off offset:128
	global_load_dwordx4 v[100:103], v[0:1], off offset:160
	global_load_dwordx4 v[104:107], v[0:1], off offset:192
	global_load_dwordx4 v[108:111], v[0:1], off offset:224
	v_mov_b32_e32 v15, v189
	v_mov_b32_e32 v0, v189
	v_mov_b32_e32 v1, v189
	v_mov_b32_e32 v2, v189
	v_mov_b32_e32 v3, v189
	v_mov_b32_e32 v4, v189
	v_mov_b32_e32 v5, v189
	v_mov_b32_e32 v6, v189
	v_mov_b32_e32 v7, v189
	v_mov_b32_e32 v8, v189
	v_mov_b32_e32 v9, v189
	v_mov_b32_e32 v10, v189
	v_mov_b32_e32 v11, v189
	v_mov_b32_e32 v12, v189
	v_mov_b32_e32 v13, v189
	s_waitcnt vmcnt(0)
	ds_read_b128 v[112:115], v196
	ds_read_b128 v[116:119], v197
	ds_read_b128 v[120:123], v196 offset:2048
	ds_read_b128 v[124:127], v197 offset:2048
	ds_read_b128 v[128:131], v196 offset:4096
	ds_read_b128 v[132:135], v197 offset:4096
	ds_read_b128 v[136:139], v196 offset:6144
	ds_read_b128 v[140:143], v197 offset:6144
	v_mov_b64_e32 v[30:31], v[14:15]
	v_mov_b64_e32 v[46:47], v[14:15]
	v_mov_b64_e32 v[62:63], v[14:15]
	s_mov_b32 s78, 0
	v_lshl_add_u64 v[152:153], vcc, 0, v[188:189]
	v_lshl_add_u64 v[154:155], s[2:3], 0, v[198:199]
	v_add_u32_e32 v147, s76, v167
	v_add_u32_e32 v149, s76, v168
	v_mov_b32_e32 v172, 0xf149f2ca
	v_mov_b32_e32 v171, 0
	v_mov_b64_e32 v[28:29], v[12:13]
	v_mov_b64_e32 v[26:27], v[10:11]
	v_mov_b64_e32 v[24:25], v[8:9]
	v_mov_b64_e32 v[22:23], v[6:7]
	v_mov_b64_e32 v[20:21], v[4:5]
	v_mov_b64_e32 v[18:19], v[2:3]
	v_mov_b64_e32 v[16:17], v[0:1]
	v_mov_b64_e32 v[44:45], v[12:13]
	v_mov_b64_e32 v[42:43], v[10:11]
	v_mov_b64_e32 v[40:41], v[8:9]
	v_mov_b64_e32 v[38:39], v[6:7]
	v_mov_b64_e32 v[36:37], v[4:5]
	v_mov_b64_e32 v[34:35], v[2:3]
	v_mov_b64_e32 v[32:33], v[0:1]
	v_mov_b64_e32 v[60:61], v[12:13]
	v_mov_b64_e32 v[58:59], v[10:11]
	v_mov_b64_e32 v[56:57], v[8:9]
	v_mov_b64_e32 v[54:55], v[6:7]
	v_mov_b64_e32 v[52:53], v[4:5]
	v_mov_b64_e32 v[50:51], v[2:3]
	v_mov_b64_e32 v[48:49], v[0:1]
	s_mov_b32 s94, s68
.LBB0_1134:
	s_waitcnt lgkmcnt(0)
	v_mfma_f32_32x32x16_bf16 v[64:79], v[112:115], v[80:83], 0
	s_cmp_gt_u32 s81, 3
	s_cselect_b64 s[2:3], -1, 0
	s_and_b64 vcc, exec, s[2:3]
	v_mfma_f32_32x32x16_bf16 v[64:79], v[116:119], v[84:87], v[64:79]
	v_mfma_f32_32x32x16_bf16 v[64:79], v[120:123], v[88:91], v[64:79]
	v_mfma_f32_32x32x16_bf16 v[64:79], v[124:127], v[92:95], v[64:79]
	v_mfma_f32_32x32x16_bf16 v[64:79], v[128:131], v[96:99], v[64:79]
	v_mfma_f32_32x32x16_bf16 v[64:79], v[132:135], v[100:103], v[64:79]
	v_mfma_f32_32x32x16_bf16 v[64:79], v[136:139], v[104:107], v[64:79]
	v_mfma_f32_32x32x16_bf16 v[64:79], v[140:143], v[108:111], v[64:79]
	s_cbranch_vccnz .LBB0_1136
	v_ashrrev_i32_e32 v116, 31, v149
	v_mov_b64_e32 v[112:113], s[84:85]
	v_mad_u64_u32 v[114:115], s[0:1], s74, v149, v[112:113]
	v_mul_lo_u32 v117, s75, v149
	v_mul_lo_u32 v116, s74, v116
	v_add3_u32 v115, v117, v115, v116
	v_lshlrev_b64 v[114:115], 8, v[114:115]
	v_lshl_add_u64 v[114:115], v[154:155], 0, v[114:115]
	s_mov_b32 m0, s90
	v_lshl_add_u64 v[116:117], v[114:115], 0, s[96:97]
	global_load_lds_dwordx4 v[114:115], off
	s_add_i32 m0, s90, 0x400
	v_lshl_add_u64 v[118:119], v[114:115], 0, 64
	global_load_lds_dwordx4 v[116:117], off
	s_add_i32 m0, s90, 0x800
	s_nop 0
	global_load_lds_dwordx4 v[118:119], off
	v_lshl_add_u64 v[118:119], v[116:117], 0, 64
	s_add_i32 m0, s90, 0xc00
	s_nop 0
	global_load_lds_dwordx4 v[118:119], off
	v_lshl_add_u64 v[118:119], v[114:115], 0, s[88:89]
	s_add_i32 m0, s90, 0x1000
	v_lshl_add_u64 v[114:115], v[114:115], 0, s[100:101]
	global_load_lds_dwordx4 v[118:119], off
	v_lshl_add_u64 v[118:119], v[116:117], 0, s[88:89]
	s_add_i32 m0, s90, 0x1400
	s_nop 0
	global_load_lds_dwordx4 v[118:119], off
	s_add_i32 m0, s90, 0x1800
	s_nop 0
	global_load_lds_dwordx4 v[114:115], off
	v_lshl_add_u64 v[114:115], v[116:117], 0, s[100:101]
	s_add_i32 m0, s90, 0x1c00
	s_nop 0
	global_load_lds_dwordx4 v[114:115], off

.LBB0_1145:
	v_add_f32_e32 v73, v73, v74
	v_fmac_f32_e32 v73, v171, v72
	v_add_u32_e32 v72, 0x2000, v166
	ds_read_b64_tr_b16 v[180:181], v72 offset:0
	ds_read_b64_tr_b16 v[182:183], v72 offset:0+512
	ds_read_b64_tr_b16 v[176:177], v72 offset:0+1024
	ds_read_b64_tr_b16 v[178:179], v72 offset:0+1536
	ds_read_b64_tr_b16 v[172:173], v72 offset:0+2048
	ds_read_b64_tr_b16 v[174:175], v72 offset:0+2560
	ds_read_b64_tr_b16 v[74:75], v72 offset:0+3072
	ds_read_b64_tr_b16 v[76:77], v72 offset:0+3584
	s_waitcnt lgkmcnt(0)
	s_add_i32 s81, s81, 1
	v_mfma_f32_32x32x16_bf16 v[48:63], v[180:183], v[64:67], v[48:63]
	s_xor_b32 s78, s78, 1
	v_add_u32_e32 v147, 32, v147
	s_andn2_b64 vcc, exec, s[2:3]
	v_mfma_f32_32x32x16_bf16 v[32:47], v[172:175], v[64:67], v[32:47]
	v_mfma_f32_32x32x16_bf16 v[48:63], v[176:179], v[68:71], v[48:63]
	v_mfma_f32_32x32x16_bf16 v[32:47], v[74:77], v[68:71], v[32:47]
	ds_read_b64_tr_b16 v[180:181], v72 offset:0x1000
	ds_read_b64_tr_b16 v[182:183], v72 offset:0x1000+512
	ds_read_b64_tr_b16 v[176:177], v72 offset:0x1000+1024
	ds_read_b64_tr_b16 v[178:179], v72 offset:0x1000+1536
	ds_read_b64_tr_b16 v[172:173], v72 offset:0x1000+2048
	ds_read_b64_tr_b16 v[174:175], v72 offset:0x1000+2560
	ds_read_b64_tr_b16 v[74:75], v72 offset:0x1000+3072
	ds_read_b64_tr_b16 v[76:77], v72 offset:0x1000+3584
	s_waitcnt lgkmcnt(0)
	s_nop 0
	v_mfma_f32_32x32x16_bf16 v[16:31], v[180:183], v[64:67], v[16:31]
	v_mfma_f32_32x32x16_bf16 v[0:15], v[172:175], v[64:67], v[0:15]
	v_mfma_f32_32x32x16_bf16 v[16:31], v[176:179], v[68:71], v[16:31]
	v_mfma_f32_32x32x16_bf16 v[0:15], v[74:77], v[68:71], v[0:15]
	s_cbranch_vccz .LBB0_1148
	v_mov_b32_e32 v171, v73
	v_mov_b32_e32 v172, v145
	s_waitcnt vmcnt(0)
	ds_read_b128 v[112:115], v196
	ds_read_b128 v[116:119], v197
	ds_read_b128 v[120:123], v196 offset:2048
	ds_read_b128 v[124:127], v197 offset:2048
	ds_read_b128 v[128:131], v196 offset:4096
	ds_read_b128 v[132:135], v197 offset:4096
	ds_read_b128 v[136:139], v196 offset:6144
	ds_read_b128 v[140:143], v197 offset:6144
	v_ashrrev_i32_e32 v180, 31, v149
	v_mov_b64_e32 v[176:177], s[84:85]
	v_mad_u64_u32 v[178:179], s[0:1], s74, v149, v[176:177]
	v_mul_lo_u32 v181, s75, v149
	v_mul_lo_u32 v180, s74, v180
	v_add3_u32 v179, v181, v179, v180
	v_lshlrev_b64 v[178:179], 8, v[178:179]
	v_lshl_add_u64 v[178:179], v[152:153], 0, v[178:179]
	s_add_i32 m0, s90, 0x2000
	v_lshl_add_u64 v[180:181], v[178:179], 0, s[96:97]
	global_load_lds_dwordx4 v[178:179], off
	s_add_i32 m0, s90, 0x2400
	v_lshl_add_u64 v[182:183], v[178:179], 0, 64
	global_load_lds_dwordx4 v[180:181], off
	s_add_i32 m0, s90, 0x2800
	s_nop 0
	global_load_lds_dwordx4 v[182:183], off
	v_lshl_add_u64 v[182:183], v[180:181], 0, 64
	s_add_i32 m0, s90, 0x2c00
	s_nop 0
	global_load_lds_dwordx4 v[182:183], off
	v_lshl_add_u64 v[182:183], v[178:179], 0, s[88:89]
	s_add_i32 m0, s90, 0x3000
	v_lshl_add_u64 v[178:179], v[178:179], 0, s[100:101]
	global_load_lds_dwordx4 v[182:183], off
	v_lshl_add_u64 v[182:183], v[180:181], 0, s[88:89]
	s_add_i32 m0, s90, 0x3400
	s_nop 0
	global_load_lds_dwordx4 v[182:183], off
	s_add_i32 m0, s90, 0x3800
	s_nop 0
	global_load_lds_dwordx4 v[178:179], off
	v_lshl_add_u64 v[178:179], v[180:181], 0, s[100:101]
	s_add_i32 m0, s90, 0x3c00
	s_nop 0
	global_load_lds_dwordx4 v[178:179], off
	v_add_u32_e32 v149, 32, v149
	s_branch .LBB0_1134
